# diff loop variant 9: V reads first, all K fragment reads early into staging/score registers, global loads at the P.V start; stacked with MLA variant 3
# baseline (speedup 1.0000x reference)
.LBB0_147:
	s_bitcmp1_b32 s1, 0
	s_cselect_b32 s0, 0x9000, 0
	s_andn2_b32 s8, 1, s1
	v_add_u32_e32 v160, s0, v235
	s_mul_i32 s8, s8, 0x9000
	v_add3_u32 v160, v160, v236, v237
	v_xor_b32_e32 v161, 32, v238
	v_add_u32_e32 v245, v160, v161
	v_xor_b32_e32 v161, 64, v238
	v_add_u32_e32 v244, v160, v161
	v_xor_b32_e32 v161, 0x60, v238
	v_add_u32_e32 v243, v160, v161
	v_xor_b32_e32 v161, 0x80, v238
	v_add_u32_e32 v242, v160, v161
	v_xor_b32_e32 v161, 0xa0, v238
	v_add_u32_e32 v241, v160, v161
	v_xor_b32_e32 v161, 0xc0, v238
	v_add_u32_e32 v240, v160, v161
	v_xor_b32_e32 v161, 0xe0, v238
	v_add_u32_e32 v246, v160, v238
	v_add_u32_e32 v239, v160, v161
	ds_read_b64_tr_b16 v[156:157], v246 offset:20480
	ds_read_b64_tr_b16 v[158:159], v246 offset:21504
	ds_read_b64_tr_b16 v[152:153], v245 offset:20480
	ds_read_b64_tr_b16 v[154:155], v245 offset:21504
	ds_read_b64_tr_b16 v[148:149], v244 offset:20480
	ds_read_b64_tr_b16 v[150:151], v244 offset:21504
	ds_read_b64_tr_b16 v[144:145], v243 offset:20480
	ds_read_b64_tr_b16 v[146:147], v243 offset:21504
	ds_read_b64_tr_b16 v[140:141], v242 offset:20480
	ds_read_b64_tr_b16 v[142:143], v242 offset:21504
	ds_read_b64_tr_b16 v[136:137], v241 offset:20480
	ds_read_b64_tr_b16 v[138:139], v241 offset:21504
	ds_read_b64_tr_b16 v[132:133], v240 offset:20480
	ds_read_b64_tr_b16 v[134:135], v240 offset:21504
	ds_read_b64_tr_b16 v[128:129], v239 offset:20480
	ds_read_b64_tr_b16 v[130:131], v239 offset:21504
	v_add3_u32 v160, s8, v205, v207
	v_add3_u32 v161, s8, v227, v228
	v_add3_u32 v247, s0, v192, v233
	s_waitcnt vmcnt(3)
	ds_write_b128 v160, v[16:19]
	v_add_u32_e32 v160, s8, v209
	s_waitcnt vmcnt(2)
	ds_write_b128 v161, v[20:23]
	v_add3_u32 v160, v160, v211, v229
	v_add_u32_e32 v161, s8, v230
	s_waitcnt vmcnt(1)
	ds_write_b128 v160, v[24:27] offset:20480
	v_add3_u32 v161, v161, v231, v232
	s_waitcnt vmcnt(0)
	ds_write_b128 v161, v[28:31] offset:20480
	ds_read_b128 v[184:187], v247
	ds_read_b128 v[168:171], v247 offset:128
	ds_read_b128 v[16:19], v247 offset:64
	ds_read_b128 v[20:23], v247 offset:192
	ds_read_b128 v[24:27], v247 offset:1280
	ds_read_b128 v[28:31], v247 offset:1408
	ds_read_b128 v[248:251], v247 offset:1344
	ds_read_b128 v[180:183], v247 offset:1472
	ds_read_b128 v[164:167], v247 offset:10240
	ds_read_b128 v[172:175], v247 offset:10368
	ds_read_b128 v[176:179], v247 offset:10304
	s_waitcnt lgkmcnt(10)
	v_mfma_f32_16x16x32_bf16 v[188:191], v[184:187], v[0:3], v[40:43]
	s_waitcnt lgkmcnt(9)
	v_mfma_f32_16x16x32_bf16 v[160:163], v[168:171], v[8:11], v[44:47]
	s_waitcnt lgkmcnt(8)
	v_mfma_f32_16x16x32_bf16 v[188:191], v[16:19], v[4:7], v[188:191]
	ds_read_b128 v[16:19], v247 offset:10432
	s_waitcnt lgkmcnt(8)
	v_mfma_f32_16x16x32_bf16 v[160:163], v[20:23], v[12:15], v[160:163]
	ds_read_b128 v[20:23], v247 offset:11520
	s_waitcnt lgkmcnt(8)
	v_mfma_f32_16x16x32_bf16 v[184:187], v[24:27], v[0:3], v[40:43]
	ds_read_b128 v[24:27], v247 offset:11648
	s_waitcnt lgkmcnt(8)
	v_mfma_f32_16x16x32_bf16 v[168:171], v[28:31], v[8:11], v[44:47]
	ds_read_b128 v[28:31], v247 offset:11584
	s_waitcnt lgkmcnt(8)
	v_mfma_f32_16x16x32_bf16 v[184:187], v[248:251], v[4:7], v[184:187]
	ds_read_b128 v[248:251], v247 offset:11712
	s_waitcnt lgkmcnt(8)
	v_mfma_f32_16x16x32_bf16 v[168:171], v[180:183], v[12:15], v[168:171]
	s_waitcnt lgkmcnt(7)
	v_mfma_f32_16x16x32_bf16 v[180:183], v[164:167], v[0:3], v[40:43]
	s_waitcnt lgkmcnt(6)
	v_mfma_f32_16x16x32_bf16 v[164:167], v[172:175], v[8:11], v[44:47]
	s_waitcnt lgkmcnt(5)
	v_mfma_f32_16x16x32_bf16 v[180:183], v[176:179], v[4:7], v[180:183]
	s_waitcnt lgkmcnt(4)
	v_mfma_f32_16x16x32_bf16 v[164:167], v[16:19], v[12:15], v[164:167]
	s_waitcnt lgkmcnt(3)
	v_mfma_f32_16x16x32_bf16 v[172:175], v[20:23], v[0:3], v[40:43]
	s_waitcnt lgkmcnt(2)
	v_mfma_f32_16x16x32_bf16 v[176:179], v[24:27], v[8:11], v[44:47]
	s_waitcnt lgkmcnt(1)
	v_mfma_f32_16x16x32_bf16 v[172:175], v[28:31], v[4:7], v[172:175]
	s_waitcnt lgkmcnt(0)
	v_mfma_f32_16x16x32_bf16 v[176:179], v[248:251], v[12:15], v[176:179]
	s_add_i32 s8, s1, 1
	s_cmp_ge_u32 s8, s82
	s_cbranch_scc1 .LBB0_153
	s_cmp_lg_u32 s1, 0
	s_cselect_b64 s[0:1], -1, 0
	s_and_b32 s9, s8, 3
	s_cmp_lg_u32 s9, 0
	s_cselect_b64 s[14:15], -1, 0
	s_and_b64 s[0:1], s[0:1], s[14:15]
	s_and_b64 vcc, exec, s[0:1]
	s_cbranch_vccnz .LBB0_153
	v_max_f32_e32 v194, v189, v189
	v_max_f32_e32 v195, v188, v188
	v_max_f32_e32 v194, v195, v194
	v_max3_f32 v194, v194, v190, v191
	v_max3_f32 v194, v194, v184, v185
	v_max3_f32 v194, v194, v186, v187
	v_max3_f32 v194, v194, v180, v181
	v_max3_f32 v194, v194, v182, v183
	v_max3_f32 v194, v194, v172, v173
	v_max3_f32 v194, v194, v174, v175
	v_mov_b32_e32 v195, v194
	s_nop 1
	v_permlane16_swap_b32_e32 v194, v195
	v_max_f32_e32 v195, v195, v195
	v_max_f32_e32 v194, v194, v194
	v_max_f32_e32 v194, v194, v195
	v_mov_b32_e32 v195, v194
	s_nop 1
	v_permlane32_swap_b32_e32 v194, v195
	v_max_f32_e32 v195, v195, v195
	v_max_f32_e32 v194, v194, v194
	v_max_f32_e32 v247, v194, v195
	v_cmp_lt_f32_e32 vcc, s44, v247
	s_cbranch_vccz .LBB0_151
	s_nop 0
	v_cndmask_b32_e32 v247, 0, v247, vcc
	v_exp_f32_e64 v194, -v247
	v_lshlrev_b32_e32 v196, 16, v72
	v_and_b32_e32 v197, 0xffff0000, v72
	v_sub_f32_e32 v191, v191, v247
	v_pk_mul_f32 v[196:197], v[194:195], v[196:197] op_sel_hi:[0,1]
	v_cvt_pk_bf16_f32 v72, v196, v197
	v_lshlrev_b32_e32 v196, 16, v73
	v_and_b32_e32 v197, 0xffff0000, v73
	v_pk_mul_f32 v[196:197], v[194:195], v[196:197] op_sel_hi:[0,1]
	v_cvt_pk_bf16_f32 v73, v196, v197
	v_lshlrev_b32_e32 v196, 16, v74
	v_and_b32_e32 v197, 0xffff0000, v74
	v_pk_mul_f32 v[196:197], v[194:195], v[196:197] op_sel_hi:[0,1]
	v_cvt_pk_bf16_f32 v74, v196, v197
	v_lshlrev_b32_e32 v196, 16, v75
	v_and_b32_e32 v197, 0xffff0000, v75
	v_pk_mul_f32 v[196:197], v[194:195], v[196:197] op_sel_hi:[0,1]
	v_cvt_pk_bf16_f32 v75, v196, v197
	v_lshlrev_b32_e32 v196, 16, v56
	v_and_b32_e32 v197, 0xffff0000, v56
	v_pk_mul_f32 v[196:197], v[194:195], v[196:197] op_sel_hi:[0,1]
	v_cvt_pk_bf16_f32 v56, v196, v197
	v_lshlrev_b32_e32 v196, 16, v57
	v_and_b32_e32 v197, 0xffff0000, v57
	v_pk_mul_f32 v[196:197], v[194:195], v[196:197] op_sel_hi:[0,1]
	v_cvt_pk_bf16_f32 v57, v196, v197
	v_lshlrev_b32_e32 v196, 16, v58
	v_and_b32_e32 v197, 0xffff0000, v58
	v_pk_mul_f32 v[196:197], v[194:195], v[196:197] op_sel_hi:[0,1]
	v_cvt_pk_bf16_f32 v58, v196, v197
	v_lshlrev_b32_e32 v196, 16, v59
	v_and_b32_e32 v197, 0xffff0000, v59
	v_pk_mul_f32 v[110:111], v[110:111], v[194:195] op_sel_hi:[1,0]
	v_pk_mul_f32 v[108:109], v[108:109], v[194:195] op_sel_hi:[1,0]
	v_pk_mul_f32 v[122:123], v[122:123], v[194:195] op_sel_hi:[1,0]
	v_pk_mul_f32 v[120:121], v[120:121], v[194:195] op_sel_hi:[1,0]
	v_pk_mul_f32 v[114:115], v[114:115], v[194:195] op_sel_hi:[1,0]
	v_pk_mul_f32 v[112:113], v[112:113], v[194:195] op_sel_hi:[1,0]
	v_pk_mul_f32 v[98:99], v[98:99], v[194:195] op_sel_hi:[1,0]
	v_pk_mul_f32 v[96:97], v[96:97], v[194:195] op_sel_hi:[1,0]
	v_pk_mul_f32 v[86:87], v[86:87], v[194:195] op_sel_hi:[1,0]
	v_pk_mul_f32 v[84:85], v[84:85], v[194:195] op_sel_hi:[1,0]
	v_pk_mul_f32 v[70:71], v[70:71], v[194:195] op_sel_hi:[1,0]
	v_pk_mul_f32 v[68:69], v[68:69], v[194:195] op_sel_hi:[1,0]
	v_pk_mul_f32 v[62:63], v[62:63], v[194:195] op_sel_hi:[1,0]
	v_pk_mul_f32 v[60:61], v[60:61], v[194:195] op_sel_hi:[1,0]
	v_pk_mul_f32 v[50:51], v[50:51], v[194:195] op_sel_hi:[1,0]
	v_pk_mul_f32 v[48:49], v[48:49], v[194:195] op_sel_hi:[1,0]
	v_pk_mul_f32 v[34:35], v[34:35], v[194:195] op_sel_hi:[1,0]
	v_pk_mul_f32 v[32:33], v[32:33], v[194:195] op_sel_hi:[1,0]
	v_pk_mul_f32 v[194:195], v[194:195], v[196:197] op_sel_hi:[0,1]
	v_sub_f32_e32 v190, v190, v247
	v_sub_f32_e32 v189, v189, v247
	v_sub_f32_e32 v188, v188, v247
	v_sub_f32_e32 v187, v187, v247
	v_sub_f32_e32 v186, v186, v247
	v_sub_f32_e32 v185, v185, v247
	v_sub_f32_e32 v184, v184, v247
	v_sub_f32_e32 v183, v183, v247
	v_sub_f32_e32 v182, v182, v247
	v_sub_f32_e32 v181, v181, v247
	v_sub_f32_e32 v180, v180, v247
	v_sub_f32_e32 v175, v175, v247
	v_sub_f32_e32 v174, v174, v247
	v_sub_f32_e32 v173, v173, v247
	v_sub_f32_e32 v172, v172, v247
	v_cvt_pk_bf16_f32 v59, v194, v195
	v_sub_f32_e32 v43, v43, v247
	v_sub_f32_e32 v42, v42, v247
	v_sub_f32_e32 v41, v41, v247
	v_sub_f32_e32 v40, v40, v247

.LBB0_153:
	v_add_f32_e32 v108, v108, v109
	v_add_f32_e32 v92, v92, v93
	s_waitcnt lgkmcnt(14)
	s_add_i32 s9, s8, 2
	s_add_i32 s14, s8, 1
	s_min_u32 s9, s9, s83
	s_min_u32 s14, s14, s83
	s_lshl_b32 s9, s9, 6
	s_lshl_b32 s14, s14, 6
	v_add_u32_e32 v16, s9, v204
	v_add_u32_e32 v20, s9, v206
	v_add_u32_e32 v24, s14, v208
	v_add_u32_e32 v28, s14, v210
	v_ashrrev_i32_e32 v17, 31, v16
	v_ashrrev_i32_e32 v21, 31, v20
	v_ashrrev_i32_e32 v25, 31, v24
	v_ashrrev_i32_e32 v29, 31, v28
	v_lshlrev_b64 v[16:17], 11, v[16:17]
	v_lshlrev_b64 v[20:21], 11, v[20:21]
	v_lshlrev_b64 v[24:25], 11, v[24:25]
	v_lshlrev_b64 v[28:29], 11, v[28:29]
	v_lshl_add_u64 v[16:17], v[212:213], 0, v[16:17]
	v_lshl_add_u64 v[20:21], v[214:215], 0, v[20:21]
	v_lshl_add_u64 v[24:25], v[216:217], 0, v[24:25]
	v_lshl_add_u64 v[28:29], v[218:219], 0, v[28:29]
	global_load_dwordx4 v[16:19], v[16:17], off
	global_load_dwordx4 v[20:23], v[20:21], off
	global_load_dwordx4 v[24:27], v[24:25], off offset:1024
	global_load_dwordx4 v[28:31], v[28:29], off offset:1024
	v_mfma_f32_16x16x32_bf16 v[120:123], v[156:159], v[72:75], v[120:123]
	v_exp_f32_e32 v188, v188
	v_exp_f32_e32 v189, v189
	v_mfma_f32_16x16x32_bf16 v[124:127], v[156:159], v[100:103], v[124:127]
	v_add_f32_e32 v109, v188, v189
	ds_read_b64_tr_b16 v[156:157], v246 offset:28672
	ds_read_b64_tr_b16 v[158:159], v246 offset:29696
	s_waitcnt lgkmcnt(14)
	v_mfma_f32_16x16x32_bf16 v[112:115], v[152:155], v[72:75], v[112:115]
	v_exp_f32_e32 v190, v190
	v_exp_f32_e32 v191, v191
	v_mfma_f32_16x16x32_bf16 v[116:119], v[152:155], v[100:103], v[116:119]
	v_add_f32_e32 v109, v109, v190
	v_add_f32_e32 v109, v109, v191
	ds_read_b64_tr_b16 v[152:153], v245 offset:28672
	ds_read_b64_tr_b16 v[154:155], v245 offset:29696
	s_waitcnt lgkmcnt(14)
	v_mfma_f32_16x16x32_bf16 v[96:99], v[148:151], v[72:75], v[96:99]
	v_exp_f32_e32 v184, v184
	v_exp_f32_e32 v185, v185
	v_mfma_f32_16x16x32_bf16 v[104:107], v[148:151], v[100:103], v[104:107]
	v_add_f32_e32 v109, v109, v184
	v_add_f32_e32 v109, v109, v185
	ds_read_b64_tr_b16 v[148:149], v244 offset:28672
	ds_read_b64_tr_b16 v[150:151], v244 offset:29696
	s_waitcnt lgkmcnt(14)
	v_mfma_f32_16x16x32_bf16 v[84:87], v[144:147], v[72:75], v[84:87]
	v_exp_f32_e32 v186, v186
	v_exp_f32_e32 v187, v187
	v_mfma_f32_16x16x32_bf16 v[88:91], v[144:147], v[100:103], v[88:91]
	v_add_f32_e32 v109, v109, v186
	v_add_f32_e32 v109, v109, v187
	ds_read_b64_tr_b16 v[144:145], v243 offset:28672
	ds_read_b64_tr_b16 v[146:147], v243 offset:29696
	s_waitcnt lgkmcnt(14)
	v_mfma_f32_16x16x32_bf16 v[68:71], v[140:143], v[72:75], v[68:71]
	v_exp_f32_e32 v194, v180
	v_exp_f32_e32 v195, v181
	v_mfma_f32_16x16x32_bf16 v[76:79], v[140:143], v[100:103], v[76:79]
	v_add_f32_e32 v109, v109, v194
	v_add_f32_e32 v109, v109, v195
	ds_read_b64_tr_b16 v[140:141], v242 offset:28672
	ds_read_b64_tr_b16 v[142:143], v242 offset:29696
	s_waitcnt lgkmcnt(14)
	v_mfma_f32_16x16x32_bf16 v[60:63], v[136:139], v[72:75], v[60:63]
	v_exp_f32_e32 v196, v182
	v_exp_f32_e32 v197, v183
	v_mfma_f32_16x16x32_bf16 v[64:67], v[136:139], v[100:103], v[64:67]
	v_add_f32_e32 v109, v109, v196
	v_add_f32_e32 v109, v109, v197
	ds_read_b64_tr_b16 v[136:137], v241 offset:28672
	ds_read_b64_tr_b16 v[138:139], v241 offset:29696
	s_waitcnt lgkmcnt(14)
	v_mfma_f32_16x16x32_bf16 v[48:51], v[132:135], v[72:75], v[48:51]
	v_exp_f32_e32 v172, v172
	v_exp_f32_e32 v173, v173
	v_mfma_f32_16x16x32_bf16 v[52:55], v[132:135], v[100:103], v[52:55]
	v_add_f32_e32 v109, v109, v172
	v_add_f32_e32 v109, v109, v173
	ds_read_b64_tr_b16 v[132:133], v240 offset:28672
	ds_read_b64_tr_b16 v[134:135], v240 offset:29696
	s_waitcnt lgkmcnt(14)
	v_mfma_f32_16x16x32_bf16 v[32:35], v[128:131], v[72:75], v[32:35]
	ds_read_b64_tr_b16 v[180:181], v239 offset:28672
	ds_read_b64_tr_b16 v[182:183], v239 offset:29696
	v_exp_f32_e32 v174, v174
	v_exp_f32_e32 v175, v175
	v_mfma_f32_16x16x32_bf16 v[36:39], v[128:131], v[100:103], v[36:39]
	v_add_f32_e32 v109, v109, v174
	v_add_f32_e32 v109, v109, v175
	s_waitcnt lgkmcnt(14)
	v_mfma_f32_16x16x32_bf16 v[120:123], v[156:159], v[56:59], v[120:123]
	v_exp_f32_e32 v100, v160
	v_exp_f32_e32 v101, v161
	v_cvt_pk_bf16_f32 v72, v188, v189
	v_mfma_f32_16x16x32_bf16 v[124:127], v[156:159], v[80:83], v[124:127]
	v_add_f32_e32 v93, v100, v101
	v_cvt_pk_bf16_f32 v73, v190, v191
	v_cvt_pk_bf16_f32 v74, v184, v185
	v_cvt_pk_bf16_f32 v75, v186, v187
	s_waitcnt lgkmcnt(12)
	v_mfma_f32_16x16x32_bf16 v[112:115], v[152:155], v[56:59], v[112:115]
	v_exp_f32_e32 v102, v162
	v_exp_f32_e32 v103, v163
	v_mfma_f32_16x16x32_bf16 v[116:119], v[152:155], v[80:83], v[116:119]
	v_add_f32_e32 v93, v93, v102
	v_add_f32_e32 v93, v93, v103
	s_waitcnt lgkmcnt(10)
	v_mfma_f32_16x16x32_bf16 v[96:99], v[148:151], v[56:59], v[96:99]
	v_exp_f32_e32 v152, v168
	v_exp_f32_e32 v153, v169
	v_mfma_f32_16x16x32_bf16 v[104:107], v[148:151], v[80:83], v[104:107]
	v_add_f32_e32 v93, v93, v152
	v_add_f32_e32 v93, v93, v153
	s_waitcnt lgkmcnt(8)
	v_mfma_f32_16x16x32_bf16 v[84:87], v[144:147], v[56:59], v[84:87]
	v_exp_f32_e32 v148, v170
	v_exp_f32_e32 v149, v171
	v_mfma_f32_16x16x32_bf16 v[88:91], v[144:147], v[80:83], v[88:91]
	v_add_f32_e32 v93, v93, v148
	v_add_f32_e32 v93, v93, v149
	s_waitcnt lgkmcnt(6)
	v_mfma_f32_16x16x32_bf16 v[68:71], v[140:143], v[56:59], v[68:71]
	v_cvt_pk_bf16_f32 v100, v100, v101
	v_cvt_pk_bf16_f32 v101, v102, v103
	v_cvt_pk_bf16_f32 v102, v152, v153
	v_mfma_f32_16x16x32_bf16 v[76:79], v[140:143], v[80:83], v[76:79]
	v_cvt_pk_bf16_f32 v103, v148, v149
	v_exp_f32_e32 v140, v164
	v_exp_f32_e32 v141, v165
	s_waitcnt lgkmcnt(4)
	v_mfma_f32_16x16x32_bf16 v[60:63], v[136:139], v[56:59], v[60:63]
	v_add_f32_e32 v93, v93, v140
	v_add_f32_e32 v93, v93, v141
	v_exp_f32_e32 v142, v166
	v_exp_f32_e32 v143, v167
	v_mfma_f32_16x16x32_bf16 v[64:67], v[136:139], v[80:83], v[64:67]
	v_add_f32_e32 v93, v93, v142
	v_add_f32_e32 v93, v93, v143
	s_waitcnt lgkmcnt(2)
	v_mfma_f32_16x16x32_bf16 v[48:51], v[132:135], v[56:59], v[48:51]
	v_exp_f32_e32 v136, v176
	v_exp_f32_e32 v137, v177
	v_mfma_f32_16x16x32_bf16 v[52:55], v[132:135], v[80:83], v[52:55]
	v_add_f32_e32 v93, v93, v136
	v_add_f32_e32 v93, v93, v137
	s_waitcnt lgkmcnt(0)
	v_mfma_f32_16x16x32_bf16 v[32:35], v[180:183], v[56:59], v[32:35]
	v_exp_f32_e32 v132, v178
	v_exp_f32_e32 v133, v179
	v_mfma_f32_16x16x32_bf16 v[36:39], v[180:183], v[80:83], v[36:39]
	v_add_f32_e32 v93, v93, v132
	v_add_f32_e32 v93, v93, v133
	s_waitcnt lgkmcnt(0)
	s_barrier
	v_cvt_pk_bf16_f32 v56, v194, v195
	v_cvt_pk_bf16_f32 v57, v196, v197
	v_cvt_pk_bf16_f32 v58, v172, v173
	v_cvt_pk_bf16_f32 v59, v174, v175
	v_cvt_pk_bf16_f32 v80, v140, v141
	v_cvt_pk_bf16_f32 v81, v142, v143
	v_cvt_pk_bf16_f32 v82, v136, v137
	v_cvt_pk_bf16_f32 v83, v132, v133
	s_cmp_lg_u32 s82, s8
	s_cbranch_scc0 .LBB0_139
	s_mov_b32 s1, s8
	s_branch .LBB0_147
